# P7 normmod: gamma/scale/shift loads of pieces 2-7 hoisted (18 loads in flight, one wait) instead of 6 serial round trips per row; plus c3
# speedup vs baseline: 1.0026x; 1.0026x over previous
; __device__ __forceinline__ void normmod_phase(const float* xp, const float* xs, const float* g, const float* mod, int sh_off, int sc_off, bf16_t* dst, int lane, int wave) {
;     ...
;     for (int r = gw; r < TT; r += NGW) {
;         const float* xrow = r < TP ? xp + (size_t)r * DM : xs + (size_t)(r - TP) * DM;
;         const int b = r < TP ? 0 : 1 + ((r - TP) >> 6);
;         const f32x4* xr = (const f32x4*)xrow + lane;
;         f32x4 v[8]; float s = 0.f;
; #pragma unroll
;         for (int j = 0; j < 8; ++j) { v[j] = __builtin_nontemporal_load(xr + 64 * j); s += (v[j].x * v[j].x + v[j].y * v[j].y) + (v[j].z * v[j].z + v[j].w * v[j].w); }
;         const float rstd = rsqrtf(wave_sum(s) * (1.f / DM) + EPS);
.LBB0_2139:
	global_load_dwordx4 v[52:55], v28, s[18:19] nt
	global_load_dwordx4 v[20:23], v28, s[18:19] offset:1024 nt
	global_load_dwordx4 v[24:27], v28, s[18:19] offset:2048 nt
	global_load_dwordx4 v[16:19], v28, s[18:19] offset:3072 nt
	v_lshl_add_u64 v[0:1], s[18:19], 0, v[28:29]
	v_add_co_u32_e32 v42, vcc, s24, v0
	s_lshr_b32 s4, s4, 6
	s_nop 0
	v_addc_co_u32_e32 v43, vcc, 0, v1, vcc
	global_load_dwordx4 v[8:11], v[42:43], off nt
	global_load_dwordx4 v[12:15], v[42:43], off offset:1024 nt
	global_load_dwordx4 v[0:3], v[42:43], off offset:3072 nt
	global_load_dwordx4 v[4:7], v[42:43], off offset:2048 nt
	s_add_i32 s4, s4, 1
	s_and_b64 s[16:17], s[16:17], exec
	s_cselect_b32 s4, 0, s4
	s_mul_hi_u32 s17, s4, 0xc000
	s_mul_i32 s4, s4, 0xc000
	s_add_u32 s16, s70, s4
	s_addc_u32 s17, s71, s17
	v_lshl_add_u64 v[68:69], s[16:17], 0, v[28:29]
	v_add_co_u32_e32 v42, vcc, s26, v68
	global_load_dwordx4 v[56:59], v[30:31], off
	s_nop 0
	v_addc_co_u32_e32 v43, vcc, 0, v69, vcc
	v_add_co_u32_e32 v70, vcc, s27, v68
	s_lshl_b64 s[14:15], s[14:15], 12
	s_nop 0
	v_addc_co_u32_e32 v71, vcc, 0, v69, vcc
	global_load_dwordx4 v[60:63], v[42:43], off offset:-4096
	global_load_dwordx4 v[64:67], v[70:71], off offset:-4096
	s_add_u32 s0, s0, s2
	s_addc_u32 s1, s1, s3
	s_add_u32 s6, s6, s8
	s_addc_u32 s7, s7, s9
	s_cmpk_lt_i32 s0, 0x4200
	s_waitcnt vmcnt(0)
	v_mov_b32_e32 v74, v53
	v_mov_b32_e32 v75, v21
	v_mov_b32_e32 v78, v55
	v_mov_b32_e32 v79, v23
	v_mov_b32_e32 v72, v52
	v_mov_b32_e32 v73, v20
	v_mov_b32_e32 v76, v54
	v_mov_b32_e32 v77, v22
	v_pk_mul_f32 v[80:81], v[26:27], v[26:27]
	v_pk_mul_f32 v[82:83], v[24:25], v[24:25]
	v_pk_mul_f32 v[74:75], v[74:75], v[74:75]
	v_pk_mul_f32 v[78:79], v[78:79], v[78:79]
	v_pk_mov_b32 v[88:89], v[82:83], v[80:81] op_sel:[1,0]
	v_mov_b32_e32 v83, v81
	v_pk_fma_f32 v[72:73], v[72:73], v[72:73], v[74:75]
	v_pk_fma_f32 v[74:75], v[76:77], v[76:77], v[78:79]
	v_mul_f32_e32 v84, v17, v17
	v_mul_f32_e32 v86, v19, v19
	v_pk_add_f32 v[76:77], v[88:89], v[82:83]
	v_pk_add_f32 v[72:73], v[72:73], v[74:75]
	v_pk_fma_f32 v[80:81], v[16:17], v[16:17], v[84:85] op_sel_hi:[1,1,0]
	v_pk_fma_f32 v[84:85], v[18:19], v[18:19], v[86:87] op_sel_hi:[1,1,0]
	v_mul_f32_e32 v51, v8, v8
	v_mul_f32_e32 v89, v9, v9
	v_pk_add_f32 v[74:75], v[76:77], v[76:77] op_sel:[0,1] op_sel_hi:[1,0]
	v_pk_add_f32 v[72:73], v[72:73], v[72:73] op_sel:[0,1] op_sel_hi:[1,0]
	v_mul_f32_e32 v81, v10, v10
	v_mul_f32_e32 v85, v11, v11
	v_pk_mul_f32 v[78:79], v[14:15], v[14:15]
	v_pk_mul_f32 v[82:83], v[12:13], v[12:13]
	v_mov_b32_e32 v75, v89
	v_mov_b32_e32 v73, v51
	v_pk_mov_b32 v[76:77], v[82:83], v[78:79] op_sel:[1,0]
	v_mov_b32_e32 v83, v79
	v_pk_add_f32 v[80:81], v[80:81], v[84:85]
	v_pk_add_f32 v[72:73], v[72:73], v[74:75]
	v_mul_f32_e32 v86, v5, v5
	v_mul_f32_e32 v88, v7, v7
	v_pk_add_f32 v[76:77], v[76:77], v[82:83]
	v_pk_add_f32 v[72:73], v[72:73], v[80:81]
	v_mul_f32_e32 v90, v0, v0
	v_mul_f32_e32 v91, v1, v1
	v_mul_f32_e32 v92, v2, v2
	v_mul_f32_e32 v93, v3, v3
	v_pk_fma_f32 v[78:79], v[4:5], v[4:5], v[86:87] op_sel_hi:[1,1,0]
	v_pk_fma_f32 v[86:87], v[6:7], v[6:7], v[88:89] op_sel_hi:[1,1,0]
	v_pk_add_f32 v[76:77], v[76:77], v[76:77] op_sel:[0,1] op_sel_hi:[1,0]
	v_pk_add_f32 v[72:73], v[72:73], v[72:73] op_sel:[0,1] op_sel_hi:[1,0]
	v_mov_b32_e32 v79, v92
	v_mov_b32_e32 v87, v93
	v_mov_b32_e32 v77, v91
	v_mov_b32_e32 v73, v90
	v_pk_add_f32 v[78:79], v[78:79], v[86:87]
	v_pk_add_f32 v[72:73], v[72:73], v[76:77]
	v_pk_add_f32 v[62:63], v[62:63], 1.0 op_sel_hi:[1,0]
	v_pk_add_f32 v[72:73], v[72:73], v[78:79]
	v_pk_add_f32 v[60:61], v[60:61], 1.0 op_sel_hi:[1,0]
	v_add_f32_e32 v51, v72, v73
	ds_bpermute_b32 v72, v44, v51
	s_waitcnt lgkmcnt(0)
	v_add_f32_e32 v51, v51, v72
	ds_bpermute_b32 v72, v45, v51
	s_waitcnt lgkmcnt(0)
	v_add_f32_e32 v51, v51, v72
	ds_bpermute_b32 v72, v46, v51
	s_waitcnt lgkmcnt(0)
	v_add_f32_e32 v51, v51, v72
	ds_bpermute_b32 v72, v47, v51
	s_waitcnt lgkmcnt(0)
	v_add_f32_e32 v51, v51, v72
	ds_bpermute_b32 v72, v48, v51
	s_waitcnt lgkmcnt(0)
	v_add_f32_e32 v51, v51, v72
	ds_bpermute_b32 v72, v49, v51
	s_waitcnt lgkmcnt(0)
; __device__ __forceinline__ unsigned pk2(float lo, float hi) { const f32x2v v = {lo, hi}; const bf16x2v b = __builtin_convertvector(v, bf16x2v); return __builtin_bit_cast(unsigned, b); }
; __device__ __forceinline__ void normmod_phase(const float* xp, const float* xs, const float* g, const float* mod, int sh_off, int sc_off, bf16_t* dst, int lane, int wave) {
;     ...
;         const float rstd = rsqrtf(wave_sum(s) * (1.f / DM) + EPS);
;         const f32x4* gp = (const f32x4*)g + lane; const f32x4* scp = (const f32x4*)(mod + (size_t)b * MODW + sc_off) + lane; const f32x4* shp = (const f32x4*)(mod + (size_t)b * MODW + sh_off) + lane;
;         u64* o8 = (u64*)(dst + (size_t)r * DM) + lane;
; #pragma unroll
;         for (int j = 0; j < 8; ++j) { const f32x4 gg = gp[64 * j], sc = scp[64 * j], sh = shp[64 * j];
;             const f32x4 y = v[j] * rstd * gg * (sc + 1.f) + sh;
;             o8[64 * j] = (u64)pk2(y.x, y.y) | ((u64)pk2(y.z, y.w) << 32); }
	v_add_f32_e32 v51, v51, v72
	v_fmamk_f32 v51, v51, 0x3a000000, v50
	v_mul_f32_e32 v72, 0x4b800000, v51
	v_cmp_gt_f32_e32 vcc, s25, v51
	s_nop 1
	v_cndmask_b32_e32 v51, v51, v72, vcc
	v_rsq_f32_e32 v51, v51
	v_lshl_add_u64 v[72:73], v[32:33], 0, s[14:15]
	v_mul_f32_e32 v74, 0x45800000, v51
	v_cndmask_b32_e32 v74, v51, v74, vcc
	v_pk_mul_f32 v[54:55], v[54:55], v[74:75] op_sel_hi:[1,0]
	v_pk_mul_f32 v[52:53], v[52:53], v[74:75] op_sel_hi:[1,0]
	v_pk_mul_f32 v[54:55], v[58:59], v[54:55]
	v_pk_mul_f32 v[52:53], v[56:57], v[52:53]
	v_pk_fma_f32 v[54:55], v[62:63], v[54:55], v[66:67]
	v_pk_fma_f32 v[52:53], v[60:61], v[52:53], v[64:65]
	v_lshl_add_u64 v[64:65], v[68:69], 0, s[10:11]
	v_cvt_pk_bf16_f32 v52, v52, v53
	v_cvt_pk_bf16_f32 v53, v54, v55
	global_store_dwordx2 v[72:73], v[52:53], off
	global_load_dwordx4 v[52:55], v[30:31], off offset:1024
	v_lshl_add_u64 v[66:67], v[68:69], 0, s[12:13]
	global_load_dwordx4 v[56:59], v[64:65], off offset:1024
	global_load_dwordx4 v[60:63], v[66:67], off offset:1024
	global_load_dwordx4 v[96:99], v[30:31], off offset:2048
	global_load_dwordx4 v[100:103], v[64:65], off offset:2048
	global_load_dwordx4 v[104:107], v[66:67], off offset:2048
	global_load_dwordx4 v[108:111], v[30:31], off offset:3072
	global_load_dwordx4 v[112:115], v[64:65], off offset:3072
	global_load_dwordx4 v[116:119], v[66:67], off offset:3072
	global_load_dwordx4 v[120:123], v[34:35], off
	global_load_dwordx4 v[124:127], v[42:43], off
	global_load_dwordx4 v[132:135], v[70:71], off
	global_load_dwordx4 v[136:139], v[36:37], off
	global_load_dwordx4 v[140:143], v[42:43], off offset:1024
	global_load_dwordx4 v[144:147], v[70:71], off offset:1024
	global_load_dwordx4 v[148:151], v[38:39], off
	global_load_dwordx4 v[152:155], v[42:43], off offset:2048
	global_load_dwordx4 v[156:159], v[70:71], off offset:2048
	global_load_dwordx4 v[160:163], v[40:41], off
	global_load_dwordx4 v[164:167], v[42:43], off offset:3072
	global_load_dwordx4 v[168:171], v[70:71], off offset:3072
	v_pk_mul_f32 v[22:23], v[22:23], v[74:75] op_sel_hi:[1,0]
	v_pk_mul_f32 v[20:21], v[20:21], v[74:75] op_sel_hi:[1,0]
	v_pk_mul_f32 v[26:27], v[26:27], v[74:75] op_sel_hi:[1,0]
	v_pk_mul_f32 v[24:25], v[24:25], v[74:75] op_sel_hi:[1,0]
	v_pk_mul_f32 v[18:19], v[18:19], v[74:75] op_sel_hi:[1,0]
	v_pk_mul_f32 v[16:17], v[16:17], v[74:75] op_sel_hi:[1,0]
	v_pk_mul_f32 v[10:11], v[10:11], v[74:75] op_sel_hi:[1,0]
	v_pk_mul_f32 v[8:9], v[8:9], v[74:75] op_sel_hi:[1,0]
	v_pk_mul_f32 v[14:15], v[14:15], v[74:75] op_sel_hi:[1,0]
	v_pk_mul_f32 v[12:13], v[12:13], v[74:75] op_sel_hi:[1,0]
	v_pk_mul_f32 v[6:7], v[6:7], v[74:75] op_sel_hi:[1,0]
	v_pk_mul_f32 v[4:5], v[4:5], v[74:75] op_sel_hi:[1,0]
	v_pk_mul_f32 v[2:3], v[2:3], v[74:75] op_sel_hi:[1,0]
	v_pk_mul_f32 v[0:1], v[0:1], v[74:75] op_sel_hi:[1,0]
	s_waitcnt vmcnt(20)
	v_pk_mul_f32 v[20:21], v[52:53], v[20:21]
	v_pk_mul_f32 v[22:23], v[54:55], v[22:23]
	s_waitcnt vmcnt(19)
	v_pk_add_f32 v[52:53], v[58:59], 1.0 op_sel_hi:[1,0]
	v_pk_add_f32 v[54:55], v[56:57], 1.0 op_sel_hi:[1,0]
	s_waitcnt vmcnt(18)
	v_pk_fma_f32 v[22:23], v[52:53], v[22:23], v[62:63]
	v_pk_fma_f32 v[20:21], v[54:55], v[20:21], v[60:61]
	s_nop 0
	v_cvt_pk_bf16_f32 v20, v20, v21
	v_cvt_pk_bf16_f32 v21, v22, v23
	global_store_dwordx2 v[72:73], v[20:21], off offset:512
	s_waitcnt vmcnt(0)
	v_pk_mul_f32 v[20:21], v[96:97], v[24:25]
	v_pk_mul_f32 v[22:23], v[98:99], v[26:27]
	v_pk_add_f32 v[24:25], v[102:103], 1.0 op_sel_hi:[1,0]
	v_pk_add_f32 v[26:27], v[100:101], 1.0 op_sel_hi:[1,0]
	v_pk_fma_f32 v[22:23], v[24:25], v[22:23], v[106:107]
	v_pk_fma_f32 v[20:21], v[26:27], v[20:21], v[104:105]
	s_nop 0
	v_cvt_pk_bf16_f32 v20, v20, v21
	v_cvt_pk_bf16_f32 v21, v22, v23
	global_store_dwordx2 v[72:73], v[20:21], off offset:1024
	v_pk_mul_f32 v[16:17], v[108:109], v[16:17]
	v_pk_mul_f32 v[18:19], v[110:111], v[18:19]
	v_pk_add_f32 v[20:21], v[114:115], 1.0 op_sel_hi:[1,0]
	v_pk_add_f32 v[22:23], v[112:113], 1.0 op_sel_hi:[1,0]
	v_pk_fma_f32 v[18:19], v[20:21], v[18:19], v[118:119]
	v_pk_fma_f32 v[16:17], v[22:23], v[16:17], v[116:117]
	s_nop 0
	v_cvt_pk_bf16_f32 v16, v16, v17
	v_cvt_pk_bf16_f32 v17, v18, v19
	global_store_dwordx2 v[72:73], v[16:17], off offset:1536
	v_pk_mul_f32 v[8:9], v[8:9], v[120:121]
	v_pk_mul_f32 v[10:11], v[10:11], v[122:123]
	v_pk_add_f32 v[16:17], v[126:127], 1.0 op_sel_hi:[1,0]
	v_pk_add_f32 v[18:19], v[124:125], 1.0 op_sel_hi:[1,0]
	v_pk_fma_f32 v[10:11], v[10:11], v[16:17], v[134:135]
	v_pk_fma_f32 v[8:9], v[8:9], v[18:19], v[132:133]
	s_nop 0
	v_cvt_pk_bf16_f32 v8, v8, v9
	v_cvt_pk_bf16_f32 v9, v10, v11
	global_store_dwordx2 v[72:73], v[8:9], off offset:2048
	v_pk_mul_f32 v[8:9], v[12:13], v[136:137]
	v_pk_mul_f32 v[10:11], v[14:15], v[138:139]
	v_pk_add_f32 v[12:13], v[142:143], 1.0 op_sel_hi:[1,0]
	v_pk_add_f32 v[14:15], v[140:141], 1.0 op_sel_hi:[1,0]
	v_pk_fma_f32 v[10:11], v[10:11], v[12:13], v[146:147]
	v_pk_fma_f32 v[8:9], v[8:9], v[14:15], v[144:145]
	s_nop 0
	v_cvt_pk_bf16_f32 v8, v8, v9
	v_cvt_pk_bf16_f32 v9, v10, v11
	global_store_dwordx2 v[72:73], v[8:9], off offset:2560
	v_pk_mul_f32 v[4:5], v[4:5], v[148:149]
	v_pk_mul_f32 v[6:7], v[6:7], v[150:151]
	v_pk_add_f32 v[8:9], v[154:155], 1.0 op_sel_hi:[1,0]
	v_pk_add_f32 v[10:11], v[152:153], 1.0 op_sel_hi:[1,0]
	v_pk_fma_f32 v[6:7], v[6:7], v[8:9], v[158:159]
	v_pk_fma_f32 v[4:5], v[4:5], v[10:11], v[156:157]
	s_nop 0
	v_cvt_pk_bf16_f32 v4, v4, v5
	v_cvt_pk_bf16_f32 v5, v6, v7
	global_store_dwordx2 v[72:73], v[4:5], off offset:3072
	v_pk_mul_f32 v[0:1], v[0:1], v[160:161]
	v_pk_mul_f32 v[2:3], v[2:3], v[162:163]
	v_pk_add_f32 v[4:5], v[166:167], 1.0 op_sel_hi:[1,0]
	v_pk_add_f32 v[6:7], v[164:165], 1.0 op_sel_hi:[1,0]
	v_pk_fma_f32 v[2:3], v[2:3], v[4:5], v[170:171]
	v_pk_fma_f32 v[0:1], v[0:1], v[6:7], v[168:169]
	s_nop 0
	v_cvt_pk_bf16_f32 v0, v0, v1
	v_cvt_pk_bf16_f32 v1, v2, v3
	global_store_dwordx2 v[72:73], v[0:1], off offset:3584
	s_cbranch_scc0 .LBB0_2144
